# attention PV: V^T tile written with permuted key order so each lane's fragment is one conflict-free ds_read_b128 (was ds_read2_b64 with 2-way bank conflicts)
# speedup vs baseline: 1.0355x; 1.0019x over previous
; DI float bf2f(bf16_t u) { return __uint_as_float(((unsigned)u) << 16); }
; DI float sigmoidf_(float x) { return __builtin_amdgcn_rcpf(1.f + __expf(-x)); }
; DI int tidx() { int t = threadIdx.x; asm volatile("" : "+v"(t)); return t; }
; DI char* WS(const Params&) { return *(char* const __attribute__((address_space(4)))*)(KA() + 8 * 30); }
; DI void nsa_item(const Params& p, int l_, int item, char* smraw, bool wr = true) {
;   const int qb = 31 - (item >> 4), bg = item & 15, b = bg >> 1, g = bg & 1;
;   bf16_t* Ks = (bf16_t*)smraw; bf16_t* Vs = Ks + 64 * LDT;
;   float* imp = (float*)(smraw + 18432);
;   float* scs = (float*)(smraw + 18432 + 33792);
;   unsigned* selm = (unsigned*)(smraw + 18432 + 33792 + 8448);
;   const bf16_t* hb = (const bf16_t*)(WS(p) + O_H);
;   bf16_t* hw = (bf16_t*)(WS(p) + O_H);
;   const bf16_t* vt = (const bf16_t*)(WS(p) + O_VT);
;   const int tid = tidx(), lane = tid & 63, w = (tid >> 6) & 3, qh = tid >> 8, h = lane >> 5, r31 = lane & 31;
;   const int H = g * 4 + w;
;   const int qpos = 64 * qb + 32 * qh + r31;
;   const size_t mrow = (size_t)b * 2048 + qpos;
;   const int cur = qb;
;   bf16x8 qf[4];
; #pragma unroll
;   for (int s = 0; s < 4; ++s) qf[s] = *(const bf16x8*)(hb + mrow * HS + C_AQ + H * 64 + 16 * s + 8 * h);
;   scale_q(qf);
;   const float g0 = sigmoidf_(bf2f(hb[mrow * HS + C_GATE + 0 * 8 + H]));
;   const float g1 = sigmoidf_(bf2f(hb[mrow * HS + C_GATE + 1 * 8 + H]));
;   const float g2 = sigmoidf_(bf2f(hb[mrow * HS + C_GATE + 2 * 8 + H]));
.LBB0_518:
	s_or_b64 exec, exec, s[2:3]
	v_readlane_b32 s0, v252, 49
	s_waitcnt lgkmcnt(0)
	s_barrier
	v_mov_b32_e32 v0, s0
	ds_read_b32 v0, v0
	s_movk_i32 s0, 0x31f
	s_mov_b64 s[2:3], -1
	s_waitcnt lgkmcnt(0)
	s_barrier
	v_cmp_lt_i32_e32 vcc, s0, v0
	v_readfirstlane_b32 s20, v0
	s_cbranch_vccnz .LBB0_513
	s_cmp_gt_i32 s20, 31
	s_cbranch_scc0 .LBB0_661
	s_and_b32 s23, s20, 1
	s_cmpk_gt_u32 s20, 0x11f
	s_cbranch_scc0 .LBB0_643
	s_add_i32 s0, s20, 0xfffffee0
	s_lshr_b32 s0, s0, 4
	v_writelane_b32 v252, s0, 61
	s_xor_b32 s22, s0, 31
	v_readlane_b32 s0, v252, 6
	v_readlane_b32 s1, v252, 7
	s_mov_b64 s[2:3], s[0:1]
	s_mov_b64 s[4:5], s[0:1]
	s_load_dwordx2 s[2:3], s[2:3], 0xf0
	s_load_dwordx2 s[4:5], s[4:5], 0xf0
	s_bfe_u32 s6, s20, 0x30001
	v_mov_b32_e32 v143, v201
	s_waitcnt lgkmcnt(0)
	s_add_u32 s2, s2, 0x32a4500
	s_addc_u32 s3, s3, 0
	v_writelane_b32 v252, s4, 62
	s_mov_b32 s10, s23
	s_lshl_b32 s8, s6, 11
	v_writelane_b32 v252, s5, 63
	s_mov_b64 s[4:5], s[0:1]
	s_load_dwordx2 s[4:5], s[4:5], 0xf0
	v_readlane_b32 s0, v252, 52
	v_bfe_u32 v144, v143, 6, 2
	v_ashrrev_i32_e32 v142, 3, v143
	v_lshl_or_b32 v145, s23, 2, v144
	s_lshl_b32 s23, s22, 6
	v_and_b32_e32 v141, 0xffffffe0, v142
	v_and_b32_e32 v140, 31, v143
	v_add_u32_e32 v0, s23, v141
	v_or_b32_e32 v212, v0, v140
	v_readlane_b32 s1, v252, 53
	s_mov_b32 s9, s1
	v_ashrrev_i32_e32 v213, 31, v212
	v_lshl_add_u64 v[210:211], v[212:213], 0, s[8:9]
	s_waitcnt vmcnt(0)
	v_mov_b64_e32 v[2:3], s[2:3]
	s_movk_i32 s7, 0x1e00
	v_mad_u64_u32 v[2:3], s[8:9], v210, s7, v[2:3]
	v_bfe_u32 v230, v143, 5, 1
	v_mad_i32_i24 v3, v211, s7, v3
	v_lshlrev_b32_e32 v0, 7, v145
	v_lshl_add_u64 v[4:5], v[2:3], 0, v[0:1]
	v_lshlrev_b32_e32 v0, 4, v230
	v_lshl_add_u64 v[16:17], v[4:5], 0, v[0:1]
	global_load_dwordx4 v[4:7], v[16:17], off
	global_load_dwordx4 v[8:11], v[16:17], off offset:32
	global_load_dwordx4 v[12:15], v[16:17], off offset:64
	s_nop 0
	global_load_dwordx4 v[16:19], v[16:17], off offset:96
	v_writelane_b32 v252, s0, 52
	v_lshlrev_b32_e32 v0, 1, v145
	v_lshl_add_u64 v[2:3], v[2:3], 0, v[0:1]
	v_writelane_b32 v252, s1, 53
	s_mov_b32 s0, 0x3e38aa3b
	v_writelane_b32 v251, s10, 0
	s_waitcnt vmcnt(3)
	v_lshlrev_b32_e32 v20, 16, v4
	v_and_b32_e32 v21, 0xffff0000, v4
	v_lshlrev_b32_e32 v4, 16, v5
	v_and_b32_e32 v5, 0xffff0000, v5
	v_pk_mul_f32 v[4:5], v[4:5], s[0:1] op_sel_hi:[1,0]
	v_pk_mul_f32 v[20:21], v[20:21], s[0:1] op_sel_hi:[1,0]
	v_cvt_pk_bf16_f32 v177, v4, v5
	v_lshlrev_b32_e32 v4, 16, v6
	v_and_b32_e32 v5, 0xffff0000, v6
	v_pk_mul_f32 v[4:5], v[4:5], s[0:1] op_sel_hi:[1,0]
	v_cvt_pk_bf16_f32 v176, v20, v21
	v_cvt_pk_bf16_f32 v178, v4, v5
	v_lshlrev_b32_e32 v4, 16, v7
	v_and_b32_e32 v5, 0xffff0000, v7
	v_pk_mul_f32 v[4:5], v[4:5], s[0:1] op_sel_hi:[1,0]
	s_nop 0
	v_cvt_pk_bf16_f32 v179, v4, v5
	s_waitcnt vmcnt(2)
	v_lshlrev_b32_e32 v4, 16, v8
	v_and_b32_e32 v5, 0xffff0000, v8
	v_pk_mul_f32 v[4:5], v[4:5], s[0:1] op_sel_hi:[1,0]
	s_nop 0
	v_cvt_pk_bf16_f32 v180, v4, v5
	v_lshlrev_b32_e32 v4, 16, v9
	v_and_b32_e32 v5, 0xffff0000, v9
	v_pk_mul_f32 v[4:5], v[4:5], s[0:1] op_sel_hi:[1,0]
	s_nop 0
	v_cvt_pk_bf16_f32 v181, v4, v5
	v_lshlrev_b32_e32 v4, 16, v10
	v_and_b32_e32 v5, 0xffff0000, v10
	v_pk_mul_f32 v[4:5], v[4:5], s[0:1] op_sel_hi:[1,0]
	s_nop 0
	v_cvt_pk_bf16_f32 v182, v4, v5
	v_lshlrev_b32_e32 v4, 16, v11
	v_and_b32_e32 v5, 0xffff0000, v11
	v_pk_mul_f32 v[4:5], v[4:5], s[0:1] op_sel_hi:[1,0]
	s_nop 0
	v_cvt_pk_bf16_f32 v183, v4, v5
	s_waitcnt vmcnt(1)
	v_lshlrev_b32_e32 v4, 16, v12
	v_and_b32_e32 v5, 0xffff0000, v12
	v_pk_mul_f32 v[4:5], v[4:5], s[0:1] op_sel_hi:[1,0]
	s_nop 0
	v_cvt_pk_bf16_f32 v184, v4, v5
	v_lshlrev_b32_e32 v4, 16, v13
	v_and_b32_e32 v5, 0xffff0000, v13
	v_pk_mul_f32 v[4:5], v[4:5], s[0:1] op_sel_hi:[1,0]
	s_nop 0
	v_cvt_pk_bf16_f32 v185, v4, v5
	v_lshlrev_b32_e32 v4, 16, v14
	v_and_b32_e32 v5, 0xffff0000, v14
	v_pk_mul_f32 v[4:5], v[4:5], s[0:1] op_sel_hi:[1,0]
	s_nop 0
	v_cvt_pk_bf16_f32 v186, v4, v5
	v_lshlrev_b32_e32 v4, 16, v15
	v_and_b32_e32 v5, 0xffff0000, v15
	v_pk_mul_f32 v[4:5], v[4:5], s[0:1] op_sel_hi:[1,0]
	s_nop 0
	v_cvt_pk_bf16_f32 v187, v4, v5
	s_waitcnt vmcnt(0)
	v_lshlrev_b32_e32 v4, 16, v16
	v_and_b32_e32 v5, 0xffff0000, v16
	v_pk_mul_f32 v[4:5], v[4:5], s[0:1] op_sel_hi:[1,0]
	s_nop 0
	v_cvt_pk_bf16_f32 v188, v4, v5
	v_lshlrev_b32_e32 v4, 16, v17
	v_and_b32_e32 v5, 0xffff0000, v17
	v_pk_mul_f32 v[4:5], v[4:5], s[0:1] op_sel_hi:[1,0]
	s_nop 0
	v_cvt_pk_bf16_f32 v189, v4, v5
	v_lshlrev_b32_e32 v4, 16, v18
	v_and_b32_e32 v5, 0xffff0000, v18
	v_pk_mul_f32 v[4:5], v[4:5], s[0:1] op_sel_hi:[1,0]
	s_nop 0
	v_cvt_pk_bf16_f32 v190, v4, v5
	v_lshlrev_b32_e32 v4, 16, v19
	v_and_b32_e32 v5, 0xffff0000, v19
	v_pk_mul_f32 v[4:5], v[4:5], s[0:1] op_sel_hi:[1,0]
	s_movk_i32 s0, 0x1000
	v_add_co_u32_e32 v2, vcc, s0, v2
	s_add_i32 s0, s23, 0xfffffe01
	s_nop 0
	v_addc_co_u32_e32 v3, vcc, 0, v3, vcc
	global_load_ushort v231, v[2:3], off offset:3328
	global_load_ushort v232, v[2:3], off offset:3344
	global_load_ushort v233, v[2:3], off offset:3360
	s_ashr_i32 s0, s0, 6
	s_cmp_gt_u32 s22, 7
	s_cselect_b32 s8, s0, 0
	s_mul_i32 s0, s6, 0xf00000
	s_add_u32 s2, s2, s0
	s_addc_u32 s3, s3, 0
	s_lshl_b32 s0, s10, 18
	s_lshl_b32 s1, s6, 19
	s_lshl_b32 s9, s10, 6
	s_or_b32 s0, s1, s0
	s_waitcnt lgkmcnt(0)
	s_add_u32 s0, s4, s0
	s_addc_u32 s1, s5, 0
	s_add_u32 s10, s0, 0xaaa4500
	s_addc_u32 s11, s1, 0
	v_writelane_b32 v251, s10, 1
	v_cvt_pk_bf16_f32 v191, v4, v5
	v_mov_b32_e32 v2, v201
	v_writelane_b32 v251, s11, 2
	v_writelane_b32 v251, s2, 3
	s_cmp_gt_i32 s8, s22
	v_writelane_b32 v251, s3, 4
	v_writelane_b32 v251, s9, 5
	s_cbranch_scc1 .LBB0_537
; DI int tidx() { int t = threadIdx.x; asm volatile("" : "+v"(t)); return t; }
; template <int MODE> ...
;   const int tid = tidx(), lane = tid & 63, h = lane >> 5, r31 = lane & 31;
;   const int lr = tid >> 3, lc = (tid & 7) * 8;
;   int j = jlo;
;   if (MODE == 1) { while (j <= jhi && !((uni >> j) & 1)) ++j; }
;   uint4 k0, v0;
;   if (j <= jhi) {
;     k0 = *(const uint4*)(kb + (long)(64 * j + lr) * kstride + lc);
;     v0 = *(const uint4*)(vtb + (long)lr * vstride + 64 * j + lc);
;   }
;   while (j <= jhi) {
;     __syncthreads();
;     *(uint4*)(Ks + lr * LDT + lc) = k0;
;     *(uint4*)(Vs + lr * LDT + lc) = v0;
;     __syncthreads();
;     int jn = j + 1;
;     if (MODE == 1) { while (jn <= jhi && !((uni >> jn) & 1)) ++jn; }
;     if (jn <= jhi) {
;       k0 = *(const uint4*)(kb + (long)(64 * jn + lr) * kstride + lc);
;       v0 = *(const uint4*)(vtb + (long)lr * vstride + 64 * jn + lc);
;     }
	s_lshl_b32 s0, s9, 1
	s_add_u32 s4, s2, s0
	v_ashrrev_i32_e32 v4, 3, v2
	s_addc_u32 s5, s3, 0
	s_lshl_b32 s2, s8, 6
	v_add_u32_e32 v0, s2, v4
	v_mov_b64_e32 v[6:7], s[4:5]
	v_mad_i64_i32 v[6:7], s[6:7], v0, s7, v[6:7]
	v_lshlrev_b32_e32 v0, 4, v2
	v_and_b32_e32 v0, 0x70, v0
	v_lshl_add_u64 v[6:7], v[6:7], 0, v[0:1]
	v_ashrrev_i32_e32 v5, 31, v4
	global_load_dwordx4 v[128:131], v[6:7], off offset:2048
	v_lshlrev_b64 v[6:7], 12, v[4:5]
	v_lshl_add_u64 v[6:7], s[10:11], 0, v[6:7]
	s_mov_b64 s[6:7], 0x400000
	v_lshl_add_u64 v[6:7], v[6:7], 0, s[6:7]
	s_ashr_i32 s3, s2, 31
	v_lshl_add_u64 v[8:9], s[2:3], 1, v[6:7]
	v_lshl_add_u64 v[8:9], v[8:9], 0, v[0:1]
	global_load_dwordx4 v[132:135], v[8:9], off
	s_movk_i32 s0, 0x90
	v_and_b32_e32 v3, 31, v2
	v_bfe_u32 v2, v2, 5, 1
	v_mul_lo_u32 v5, v4, s0
	v_add3_u32 v146, 0, v0, v5
	v_lshl_add_u64 v[136:137], s[4:5], 0, v[0:1]
	v_lshl_add_u64 v[138:139], v[6:7], 0, v[0:1]
	v_lshl_add_u32 v147, v2, 4, 0
	v_lshlrev_b32_e32 v0, 3, v2
	v_sub_u32_e32 v32, v147, v0
	v_mul_u32_u24_e32 v150, 0x90, v3
	v_mov_b32_e32 v30, v1
	v_mov_b32_e32 v31, v1
	v_lshlrev_b32_e32 v148, 2, v2
	v_add_u32_e32 v151, 64, v4
	v_mov_b32_e32 v0, v1
	v_mov_b32_e32 v2, v1
	v_mov_b32_e32 v3, v1
	v_mov_b32_e32 v4, v1
	v_mov_b32_e32 v5, v1
	v_mov_b32_e32 v6, v1
	v_mov_b32_e32 v7, v1
	v_mov_b32_e32 v8, v1
	v_mov_b32_e32 v9, v1
	v_mov_b32_e32 v10, v1
	v_mov_b32_e32 v11, v1
	v_mov_b32_e32 v12, v1
	v_mov_b32_e32 v13, v1
	v_mov_b32_e32 v14, v1
	v_mov_b32_e32 v15, v1
	v_mov_b32_e32 v16, v1
	v_mov_b32_e32 v17, v1
	v_mov_b32_e32 v18, v1
	v_mov_b32_e32 v19, v1
	v_mov_b32_e32 v20, v1
	v_mov_b32_e32 v21, v1
	v_mov_b32_e32 v22, v1
	v_mov_b32_e32 v23, v1
	v_mov_b32_e32 v24, v1
	v_mov_b32_e32 v25, v1
	v_mov_b32_e32 v26, v1
	v_mov_b32_e32 v27, v1
	v_mov_b32_e32 v28, v1
	v_mov_b32_e32 v29, v1
	v_add_u32_e32 v152, v147, v150
	v_mov_b64_e32 v[62:63], v[30:31]
	s_add_i32 s3, s23, 0xfffffe3f
	v_add_u32_e32 v149, 0xfffffe00, v212
	v_mov_b32_e32 v215, 0
	v_mov_b32_e32 v80, 0xf149f2ca
	v_mov_b64_e32 v[60:61], v[28:29]
	v_mov_b64_e32 v[58:59], v[26:27]
	v_mov_b64_e32 v[56:57], v[24:25]
	v_mov_b64_e32 v[54:55], v[22:23]
	v_mov_b64_e32 v[52:53], v[20:21]
	v_mov_b64_e32 v[50:51], v[18:19]
	v_mov_b64_e32 v[48:49], v[16:17]
	v_mov_b64_e32 v[46:47], v[14:15]
	v_mov_b64_e32 v[44:45], v[12:13]
	v_mov_b64_e32 v[42:43], v[10:11]
	v_mov_b64_e32 v[40:41], v[8:9]
	v_mov_b64_e32 v[38:39], v[6:7]
	v_mov_b64_e32 v[36:37], v[4:5]
	v_mov_b64_e32 v[34:35], v[2:3]
	v_mov_b64_e32 v[32:33], v[0:1]
.LBB0_523:
	s_cmp_ge_u32 s8, s22
	s_cselect_b64 s[4:5], -1, 0
	s_and_b64 vcc, exec, s[4:5]
	s_barrier
	s_waitcnt vmcnt(1)
	ds_write_b128 v146, v[128:131]
	s_waitcnt vmcnt(0)
	v_and_b32_e32 v246, 1, v201
	v_lshlrev_b32_e32 v246, 3, v246
	v_sub_u32_e32 v246, v146, v246
	v_add_u32_e32 v246, 0x2400, v246
	ds_write2_b64 v246, v[132:133], v[134:135] offset1:2
	s_waitcnt lgkmcnt(0)
	s_barrier
	s_cbranch_vccnz .LBB0_525
	s_add_i32 s6, s2, 64
	v_add_u32_e32 v0, s2, v151
	s_movk_i32 s0, 0x1e00
	v_mad_i64_i32 v[2:3], s[12:13], v0, s0, v[136:137]
	s_ashr_i32 s7, s6, 31
	global_load_dwordx4 v[128:131], v[2:3], off offset:2048
	v_lshl_add_u64 v[2:3], s[6:7], 1, v[138:139]
	global_load_dwordx4 v[132:135], v[2:3], off

; #define MFMA32(a, b, c) __builtin_amdgcn_mfma_f32_32x32x16_bf16((a), (b), (c), 0, 0, 0)
; DI unsigned pack2(float a, float b) { fv2 v = {a, b}; return __builtin_bit_cast(unsigned, __builtin_convertvector(v, bfv2)); }
; template <int MODE> ...
;     ...
; #pragma unroll
;     for (int kt = 0; kt < 2; ++kt)
; #pragma unroll
;       for (int sp = 0; sp < 2; ++sp) {
;         const bf16x8 fb = __builtin_bit_cast(bf16x8, make_uint4(pack2(s[kt][8 * sp + 0], s[kt][8 * sp + 1]), pack2(s[kt][8 * sp + 2], s[kt][8 * sp + 3]),
;                                                                pack2(s[kt][8 * sp + 4], s[kt][8 * sp + 5]), pack2(s[kt][8 * sp + 6], s[kt][8 * sp + 7])));
; #pragma unroll
;         for (int dt = 0; dt < 2; ++dt) {
;           const bf16_t* vr = Vs + (32 * dt + r31) * LDT + 32 * kt + 16 * sp + 4 * h;
;           const uint2 lo = *(const uint2*)vr; const uint2 hi = *(const uint2*)(vr + 8);
;           const bf16x8 fa = __builtin_bit_cast(bf16x8, make_uint4(lo.x, lo.y, hi.x, hi.y));
;           o[dt] = MFMA32(fa, fb, o[dt]);
;         }
;       }
.LBB0_535:
	v_add_u32_e32 v0, 0x2000, v152
	ds_read_b128 v[4:7], v0 offset:1024
	v_cvt_pk_bf16_f32 v8, v64, v65
	v_cvt_pk_bf16_f32 v9, v66, v67
	v_cvt_pk_bf16_f32 v10, v68, v69
	v_cvt_pk_bf16_f32 v11, v70, v71
	v_add_u32_e32 v3, 0x3000, v152
	s_add_i32 s8, s8, 1
	s_add_i32 s2, s2, 64
	s_andn2_b64 vcc, exec, s[4:5]
	s_waitcnt lgkmcnt(0)
	v_mfma_f32_32x32x16_bf16 v[32:47], v[4:7], v[8:11], v[32:47]
	ds_read_b128 v[4:7], v3 offset:1536
	s_waitcnt lgkmcnt(0)
	v_mfma_f32_32x32x16_bf16 v[48:63], v[4:7], v[8:11], v[48:63]
	ds_read_b128 v[4:7], v0 offset:1056
	v_cvt_pk_bf16_f32 v8, v72, v73
	v_cvt_pk_bf16_f32 v9, v74, v75
	v_cvt_pk_bf16_f32 v10, v76, v77
	v_cvt_pk_bf16_f32 v11, v78, v79
	s_waitcnt lgkmcnt(0)
	s_nop 0
	v_mfma_f32_32x32x16_bf16 v[32:47], v[4:7], v[8:11], v[32:47]
	ds_read_b128 v[4:7], v3 offset:1568
	s_waitcnt lgkmcnt(0)
	v_mfma_f32_32x32x16_bf16 v[48:63], v[4:7], v[8:11], v[48:63]
	ds_read_b128 v[4:7], v0 offset:1088
	v_cvt_pk_bf16_f32 v8, v80, v81
	v_cvt_pk_bf16_f32 v9, v82, v83
	v_cvt_pk_bf16_f32 v10, v84, v85
	v_cvt_pk_bf16_f32 v11, v86, v87
	s_waitcnt lgkmcnt(0)
	s_nop 0
	v_mfma_f32_32x32x16_bf16 v[32:47], v[4:7], v[8:11], v[32:47]
	ds_read_b128 v[4:7], v3 offset:1600
	s_waitcnt lgkmcnt(0)
	v_mfma_f32_32x32x16_bf16 v[48:63], v[4:7], v[8:11], v[48:63]
	ds_read_b128 v[4:7], v0 offset:1120
	v_cvt_pk_bf16_f32 v8, v88, v89
	v_cvt_pk_bf16_f32 v9, v90, v91
	v_cvt_pk_bf16_f32 v10, v92, v93
	v_cvt_pk_bf16_f32 v11, v94, v95
	s_waitcnt lgkmcnt(0)
	s_nop 0
	v_mfma_f32_32x32x16_bf16 v[32:47], v[4:7], v[8:11], v[32:47]
	ds_read_b128 v[4:7], v3 offset:1632
	s_waitcnt lgkmcnt(0)
	v_mfma_f32_32x32x16_bf16 v[48:63], v[4:7], v[8:11], v[48:63]
	s_cbranch_vccz .LBB0_538
	v_mov_b32_e32 v80, v2
	s_branch .LBB0_523

; DI int tidx() { int t = threadIdx.x; asm volatile("" : "+v"(t)); return t; }
; template <int MODE> ...
;   const int tid = tidx(), lane = tid & 63, h = lane >> 5, r31 = lane & 31;
;   const int lr = tid >> 3, lc = (tid & 7) * 8;
;   int j = jlo;
;   if (MODE == 1) { while (j <= jhi && !((uni >> j) & 1)) ++j; }
;   uint4 k0, v0;
;   if (j <= jhi) {
;     k0 = *(const uint4*)(kb + (long)(64 * j + lr) * kstride + lc);
;     v0 = *(const uint4*)(vtb + (long)lr * vstride + 64 * j + lc);
;   }
;   while (j <= jhi) {
;     __syncthreads();
;     *(uint4*)(Ks + lr * LDT + lc) = k0;
;     *(uint4*)(Vs + lr * LDT + lc) = v0;
;     __syncthreads();
;     int jn = j + 1;
;     if (MODE == 1) { while (jn <= jhi && !((uni >> jn) & 1)) ++jn; }
;     if (jn <= jhi) {
;       k0 = *(const uint4*)(kb + (long)(64 * jn + lr) * kstride + lc);
;       v0 = *(const uint4*)(vtb + (long)lr * vstride + 64 * jn + lc);
;     }
.LBB0_605:
	v_mov_b32_e32 v127, 0
	s_cmp_gt_u32 s10, s22
	v_mov_b32_e32 v126, 0
	v_mov_b32_e32 v125, 0
	v_mov_b32_e32 v124, 0
	v_mov_b32_e32 v123, 0
	v_mov_b32_e32 v122, 0
	v_mov_b32_e32 v121, 0
	v_mov_b32_e32 v120, 0
	v_mov_b32_e32 v119, 0
	v_mov_b32_e32 v118, 0
	v_mov_b32_e32 v117, 0
	v_mov_b32_e32 v116, 0
	v_mov_b32_e32 v115, 0
	v_mov_b32_e32 v114, 0
	v_mov_b32_e32 v113, 0
	v_mov_b32_e32 v112, 0
	v_mov_b32_e32 v111, 0
	v_mov_b32_e32 v110, 0
	v_mov_b32_e32 v109, 0
	v_mov_b32_e32 v108, 0
	v_mov_b32_e32 v107, 0
	v_mov_b32_e32 v106, 0
	v_mov_b32_e32 v105, 0
	v_mov_b32_e32 v104, 0
	v_mov_b32_e32 v103, 0
	v_mov_b32_e32 v102, 0
	v_mov_b32_e32 v101, 0
	v_mov_b32_e32 v100, 0
	v_mov_b32_e32 v99, 0
	v_mov_b32_e32 v98, 0
	v_mov_b32_e32 v97, 0
	v_mov_b32_e32 v96, 0
	v_mov_b32_e32 v214, 0
	s_cbranch_scc1 .LBB0_625
	s_movk_i32 s0, 0x90
	v_bfe_u32 v4, v2, 5, 1
	v_and_b32_e32 v5, 31, v2
	v_mul_lo_u32 v2, v216, s0
	v_readlane_b32 s0, v251, 1
	v_add3_u32 v237, 0, v0, v2
	v_lshlrev_b64 v[2:3], 12, v[216:217]
	v_readlane_b32 s1, v251, 2
	v_lshl_add_u64 v[218:219], s[38:39], 0, v[0:1]
	v_lshl_add_u32 v217, v4, 4, 0
	v_lshl_add_u64 v[2:3], s[0:1], 0, v[2:3]
	v_lshl_add_u64 v[220:221], v[2:3], 0, v[0:1]
	v_lshlrev_b32_e32 v0, 3, v4
	v_sub_u32_e32 v96, v217, v0
	v_mul_u32_u24_e32 v239, 0x90, v5
	v_mov_b32_e32 v30, v1
	v_mov_b32_e32 v31, v1
	v_lshlrev_b32_e32 v238, 2, v4
	v_mov_b32_e32 v0, v1
	v_mov_b32_e32 v2, v1
	v_mov_b32_e32 v3, v1
	v_mov_b32_e32 v4, v1
	v_mov_b32_e32 v5, v1
	v_mov_b32_e32 v6, v1
	v_mov_b32_e32 v7, v1
	v_mov_b32_e32 v8, v1
	v_mov_b32_e32 v9, v1
	v_mov_b32_e32 v10, v1
	v_mov_b32_e32 v11, v1
	v_mov_b32_e32 v12, v1
	v_mov_b32_e32 v13, v1
	v_mov_b32_e32 v14, v1
	v_mov_b32_e32 v15, v1
	v_mov_b32_e32 v16, v1
	v_mov_b32_e32 v17, v1
	v_mov_b32_e32 v18, v1
	v_mov_b32_e32 v19, v1
	v_mov_b32_e32 v20, v1
	v_mov_b32_e32 v21, v1
	v_mov_b32_e32 v22, v1
	v_mov_b32_e32 v23, v1
	v_mov_b32_e32 v24, v1
	v_mov_b32_e32 v25, v1
	v_mov_b32_e32 v26, v1
	v_mov_b32_e32 v27, v1
	v_mov_b32_e32 v28, v1
	v_mov_b32_e32 v29, v1
	v_add_u32_e32 v240, v217, v239
	v_mov_b64_e32 v[126:127], v[30:31]
	v_mov_b32_e32 v214, 0
	v_mov_b32_e32 v241, 0xf149f2ca
	v_mov_b64_e32 v[124:125], v[28:29]
	v_mov_b64_e32 v[122:123], v[26:27]
	v_mov_b64_e32 v[120:121], v[24:25]
	v_mov_b64_e32 v[118:119], v[22:23]
	v_mov_b64_e32 v[116:117], v[20:21]
	v_mov_b64_e32 v[114:115], v[18:19]
	v_mov_b64_e32 v[112:113], v[16:17]
	v_mov_b64_e32 v[110:111], v[14:15]
	v_mov_b64_e32 v[108:109], v[12:13]
	v_mov_b64_e32 v[106:107], v[10:11]
	v_mov_b64_e32 v[104:105], v[8:9]
	v_mov_b64_e32 v[102:103], v[6:7]
	v_mov_b64_e32 v[100:101], v[4:5]
	v_mov_b64_e32 v[98:99], v[2:3]
	v_mov_b64_e32 v[96:97], v[0:1]
.LBB0_607:
	s_max_i32 s0, s10, s22
	s_add_i32 s8, s0, 1
	s_mov_b32 s6, s10
	s_waitcnt lgkmcnt(0)
	s_barrier
	s_waitcnt vmcnt(1)
	ds_write_b128 v237, v[192:195]
	s_waitcnt vmcnt(0)
	v_and_b32_e32 v246, 1, v201
	v_lshlrev_b32_e32 v246, 3, v246
	v_sub_u32_e32 v246, v237, v246
	v_add_u32_e32 v246, 0x2400, v246
	ds_write2_b64 v246, v[196:197], v[198:199] offset1:2
	s_waitcnt lgkmcnt(0)
	s_barrier
	s_branch .LBB0_609

; #define MFMA32(a, b, c) __builtin_amdgcn_mfma_f32_32x32x16_bf16((a), (b), (c), 0, 0, 0)
; DI unsigned pack2(float a, float b) { fv2 v = {a, b}; return __builtin_bit_cast(unsigned, __builtin_convertvector(v, bfv2)); }
; template <int MODE> ...
;     ...
; #pragma unroll
;     for (int kt = 0; kt < 2; ++kt)
; #pragma unroll
;       for (int sp = 0; sp < 2; ++sp) {
;         const bf16x8 fb = __builtin_bit_cast(bf16x8, make_uint4(pack2(s[kt][8 * sp + 0], s[kt][8 * sp + 1]), pack2(s[kt][8 * sp + 2], s[kt][8 * sp + 3]),
;                                                                pack2(s[kt][8 * sp + 4], s[kt][8 * sp + 5]), pack2(s[kt][8 * sp + 6], s[kt][8 * sp + 7])));
; #pragma unroll
;         for (int dt = 0; dt < 2; ++dt) {
;           const bf16_t* vr = Vs + (32 * dt + r31) * LDT + 32 * kt + 16 * sp + 4 * h;
;           const uint2 lo = *(const uint2*)vr; const uint2 hi = *(const uint2*)(vr + 8);
;           const bf16x8 fa = __builtin_bit_cast(bf16x8, make_uint4(lo.x, lo.y, hi.x, hi.y));
;           o[dt] = MFMA32(fa, fb, o[dt]);
;         }
;       }
.LBB0_623:
	s_or_b64 exec, exec, s[2:3]
	v_add_u32_e32 v156, 0x2000, v240
	v_add_u32_e32 v157, 0x3000, v240
	ds_read_b128 v[132:135], v156 offset:1024
	ds_read_b128 v[136:139], v157 offset:1536
	ds_read_b128 v[140:143], v156 offset:1056
	ds_read_b128 v[144:147], v157 offset:1568
	ds_read_b128 v[148:151], v156 offset:1088
	ds_read_b128 v[152:155], v157 offset:1600
	v_cvt_pk_bf16_f32 v128, v0, v3
	v_cvt_pk_bf16_f32 v129, v2, v5
	v_cvt_pk_bf16_f32 v130, v4, v7
	v_cvt_pk_bf16_f32 v4, v12, v13
	v_cvt_pk_bf16_f32 v5, v14, v15
	v_cvt_pk_bf16_f32 v131, v6, v17
	v_cvt_pk_bf16_f32 v6, v16, v19
	v_cvt_pk_bf16_f32 v2, v8, v9
	v_cvt_pk_bf16_f32 v3, v10, v11
	v_cvt_pk_bf16_f32 v7, v18, v21
	v_cvt_pk_bf16_f32 v8, v20, v23
	v_cvt_pk_bf16_f32 v9, v22, v25
	v_cvt_pk_bf16_f32 v10, v24, v27
	v_cvt_pk_bf16_f32 v11, v26, v29
	v_cvt_pk_bf16_f32 v12, v28, v159
	v_cvt_pk_bf16_f32 v13, v30, v31
	s_xor_b64 s[0:1], s[40:41], -1
	s_and_b64 vcc, exec, s[0:1]
	s_waitcnt lgkmcnt(5)
	v_mfma_f32_32x32x16_bf16 v[96:111], v[132:135], v[128:131], v[96:111]
	s_waitcnt lgkmcnt(4)
	v_mfma_f32_32x32x16_bf16 v[112:127], v[136:139], v[128:131], v[112:127]
	ds_read_b128 v[132:135], v156 offset:1120
	ds_read_b128 v[136:139], v157 offset:1632
	s_waitcnt lgkmcnt(5)
	v_mfma_f32_32x32x16_bf16 v[96:111], v[140:143], v[2:5], v[96:111]
	s_waitcnt lgkmcnt(4)
	v_mfma_f32_32x32x16_bf16 v[112:127], v[144:147], v[2:5], v[112:127]
	s_waitcnt lgkmcnt(3)
	v_mfma_f32_32x32x16_bf16 v[96:111], v[148:151], v[6:9], v[96:111]
	s_waitcnt lgkmcnt(2)
	v_mfma_f32_32x32x16_bf16 v[112:127], v[152:155], v[6:9], v[112:127]
	s_waitcnt lgkmcnt(1)
	v_mfma_f32_32x32x16_bf16 v[96:111], v[132:135], v[10:13], v[96:111]
	s_waitcnt lgkmcnt(0)
	v_mfma_f32_32x32x16_bf16 v[112:127], v[136:139], v[10:13], v[112:127]
	s_cbranch_vccnz .LBB0_625
	v_mov_b32_e32 v241, v160
	s_mov_b32 s10, s8
	s_branch .LBB0_607

; DI int tidx() { int t = threadIdx.x; asm volatile("" : "+v"(t)); return t; }
; template <int MODE> ...
;   const int tid = tidx(), lane = tid & 63, h = lane >> 5, r31 = lane & 31;
;   const int lr = tid >> 3, lc = (tid & 7) * 8;
;   int j = jlo;
;   if (MODE == 1) { while (j <= jhi && !((uni >> j) & 1)) ++j; }
;   uint4 k0, v0;
;   if (j <= jhi) {
;     k0 = *(const uint4*)(kb + (long)(64 * j + lr) * kstride + lc);
;     v0 = *(const uint4*)(vtb + (long)lr * vstride + 64 * j + lc);
;   }
;   while (j <= jhi) {
;     __syncthreads();
;     *(uint4*)(Ks + lr * LDT + lc) = k0;
;     *(uint4*)(Vs + lr * LDT + lc) = v0;
;     __syncthreads();
;     int jn = j + 1;
;     if (MODE == 1) { while (jn <= jhi && !((uni >> jn) & 1)) ++jn; }
;     if (jn <= jhi) {
;       k0 = *(const uint4*)(kb + (long)(64 * jn + lr) * kstride + lc);
;       v0 = *(const uint4*)(vtb + (long)lr * vstride + 64 * jn + lc);
;     }
.LBB0_626:
	s_and_b64 vcc, exec, s[4:5]
	v_readlane_b32 s20, v251, 6
	s_cbranch_vccz .LBB0_642
	v_mov_b32_e32 v4, v201
	v_mov_b64_e32 v[2:3], s[38:39]
	v_ashrrev_i32_e32 v128, 3, v4
	s_movk_i32 s0, 0x1e00
	v_lshlrev_b32_e32 v0, 4, v4
	v_mad_i64_i32 v[2:3], s[0:1], v128, s0, v[2:3]
	v_and_b32_e32 v0, 0x70, v0
	v_ashrrev_i32_e32 v129, 31, v128
	v_lshl_add_u64 v[2:3], v[2:3], 0, v[0:1]
	v_readlane_b32 s0, v251, 1
	global_load_dwordx4 v[162:165], v[2:3], off offset:1536
	v_lshlrev_b64 v[2:3], 12, v[128:129]
	v_readlane_b32 s1, v251, 2
	v_lshl_add_u64 v[172:173], s[38:39], 0, v[0:1]
	v_mov_b32_e32 v30, v1
	v_lshl_add_u64 v[2:3], s[0:1], 0, v[2:3]
	v_lshl_add_u64 v[170:171], v[2:3], 0, v[0:1]
	global_load_dwordx4 v[166:169], v[170:171], off
	s_movk_i32 s0, 0x90
	v_and_b32_e32 v2, 31, v4
	v_bfe_u32 v3, v4, 5, 1
	v_mul_lo_u32 v4, v128, s0
	v_add3_u32 v174, 0, v0, v4
	v_lshl_add_u32 v175, v3, 4, 0
	v_lshlrev_b32_e32 v0, 3, v3
	v_readlane_b32 s0, v252, 61
	v_sub_u32_e32 v96, v175, v0
	s_waitcnt vmcnt(3)
	v_mul_u32_u24_e32 v194, 0x90, v2
	s_sub_i32 s6, 32, s0
	v_mov_b32_e32 v31, v1
	v_readlane_b32 s0, v252, 52
	v_lshlrev_b32_e32 v192, 2, v3
	v_mov_b32_e32 v0, v1
	v_mov_b32_e32 v2, v1
	v_mov_b32_e32 v3, v1
	v_mov_b32_e32 v4, v1
	v_mov_b32_e32 v5, v1
	v_mov_b32_e32 v6, v1
	v_mov_b32_e32 v7, v1
	v_mov_b32_e32 v8, v1
	v_mov_b32_e32 v9, v1
	v_mov_b32_e32 v10, v1
	v_mov_b32_e32 v11, v1
	v_mov_b32_e32 v12, v1
	v_mov_b32_e32 v13, v1
	v_mov_b32_e32 v14, v1
	v_mov_b32_e32 v15, v1
	v_mov_b32_e32 v16, v1
	v_mov_b32_e32 v17, v1
	v_mov_b32_e32 v18, v1
	v_mov_b32_e32 v19, v1
	v_mov_b32_e32 v20, v1
	v_mov_b32_e32 v21, v1
	v_mov_b32_e32 v22, v1
	v_mov_b32_e32 v23, v1
	v_mov_b32_e32 v24, v1
	v_mov_b32_e32 v25, v1
	v_mov_b32_e32 v26, v1
	v_mov_b32_e32 v27, v1
	v_mov_b32_e32 v28, v1
	v_mov_b32_e32 v29, v1
	v_readlane_b32 s1, v252, 53
	s_mov_b32 s0, 64
	v_add_u32_e32 v195, v175, v194
	v_mov_b64_e32 v[126:127], v[30:31]
	v_add_u32_e32 v193, -2.0, v212
	s_mov_b32 s7, 0
	v_mov_b32_e32 v214, 0
	v_mov_b32_e32 v129, 0xf149f2ca
	v_writelane_b32 v252, s0, 52
	v_mov_b64_e32 v[124:125], v[28:29]
	v_mov_b64_e32 v[122:123], v[26:27]
	v_mov_b64_e32 v[120:121], v[24:25]
	v_mov_b64_e32 v[118:119], v[22:23]
	v_mov_b64_e32 v[116:117], v[20:21]
	v_mov_b64_e32 v[114:115], v[18:19]
	v_mov_b64_e32 v[112:113], v[16:17]
	v_mov_b64_e32 v[110:111], v[14:15]
	v_mov_b64_e32 v[108:109], v[12:13]
	v_mov_b64_e32 v[106:107], v[10:11]
	v_mov_b64_e32 v[104:105], v[8:9]
	v_mov_b64_e32 v[102:103], v[6:7]
	v_mov_b64_e32 v[100:101], v[4:5]
	v_mov_b64_e32 v[98:99], v[2:3]
	v_mov_b64_e32 v[96:97], v[0:1]
	v_writelane_b32 v252, s1, 53
.LBB0_628:
	s_cmp_ge_u32 s7, s22
	s_waitcnt lgkmcnt(0)
	s_barrier
	s_waitcnt vmcnt(1)
	ds_write_b128 v174, v[162:165]
	s_waitcnt vmcnt(0)
	v_and_b32_e32 v246, 1, v201
	v_lshlrev_b32_e32 v246, 3, v246
	v_sub_u32_e32 v246, v174, v246
	v_add_u32_e32 v246, 0x2400, v246
	ds_write2_b64 v246, v[166:167], v[168:169] offset1:2
	s_waitcnt lgkmcnt(0)
	s_barrier
	s_cbranch_scc1 .LBB0_630
	v_readlane_b32 s2, v252, 52
	s_movk_i32 s0, 0x1e00
	v_readlane_b32 s3, v252, 53
	v_add_u32_e32 v0, s2, v128
	v_mad_i64_i32 v[2:3], s[0:1], v0, s0, v[172:173]
	global_load_dwordx4 v[162:165], v[2:3], off offset:1536
	v_lshl_add_u64 v[2:3], s[2:3], 1, v[170:171]
	global_load_dwordx4 v[166:169], v[2:3], off

; #define MFMA32(a, b, c) __builtin_amdgcn_mfma_f32_32x32x16_bf16((a), (b), (c), 0, 0, 0)
; DI unsigned pack2(float a, float b) { fv2 v = {a, b}; return __builtin_bit_cast(unsigned, __builtin_convertvector(v, bfv2)); }
; template <int MODE> ...
;     ...
; #pragma unroll
;     for (int kt = 0; kt < 2; ++kt)
; #pragma unroll
;       for (int sp = 0; sp < 2; ++sp) {
;         const bf16x8 fb = __builtin_bit_cast(bf16x8, make_uint4(pack2(s[kt][8 * sp + 0], s[kt][8 * sp + 1]), pack2(s[kt][8 * sp + 2], s[kt][8 * sp + 3]),
;                                                                pack2(s[kt][8 * sp + 4], s[kt][8 * sp + 5]), pack2(s[kt][8 * sp + 6], s[kt][8 * sp + 7])));
; #pragma unroll
;         for (int dt = 0; dt < 2; ++dt) {
;           const bf16_t* vr = Vs + (32 * dt + r31) * LDT + 32 * kt + 16 * sp + 4 * h;
;           const uint2 lo = *(const uint2*)vr; const uint2 hi = *(const uint2*)(vr + 8);
;           const bf16x8 fa = __builtin_bit_cast(bf16x8, make_uint4(lo.x, lo.y, hi.x, hi.y));
;           o[dt] = MFMA32(fa, fb, o[dt]);
;         }
;       }
.LBB0_640:
	v_cvt_pk_bf16_f32 v130, v0, v3
	v_add_u32_e32 v0, 0x2000, v195
	v_cvt_pk_bf16_f32 v131, v2, v5
	v_cvt_pk_bf16_f32 v132, v4, v7
	v_cvt_pk_bf16_f32 v4, v12, v13
	v_cvt_pk_bf16_f32 v5, v14, v15
	ds_read_b128 v[12:15], v0 offset:1024
	v_cvt_pk_bf16_f32 v133, v6, v129
	v_cvt_pk_bf16_f32 v6, v16, v17
	v_add_u32_e32 v16, 0x3000, v195
	s_waitcnt lgkmcnt(0)
	v_mfma_f32_32x32x16_bf16 v[96:111], v[12:15], v[130:133], v[96:111]
	ds_read_b128 v[12:15], v16 offset:1536
	v_cvt_pk_bf16_f32 v2, v8, v9
	v_cvt_pk_bf16_f32 v3, v10, v11
	v_cvt_pk_bf16_f32 v7, v18, v19
	v_cvt_pk_bf16_f32 v8, v20, v21
	v_cvt_pk_bf16_f32 v9, v22, v23
	v_cvt_pk_bf16_f32 v10, v24, v25
	s_waitcnt lgkmcnt(0)
	v_mfma_f32_32x32x16_bf16 v[112:127], v[12:15], v[130:133], v[112:127]
	ds_read_b128 v[12:15], v0 offset:1056
	v_cvt_pk_bf16_f32 v11, v26, v27
	v_readlane_b32 s0, v252, 52
	s_add_i32 s7, s7, 1
	v_readlane_b32 s1, v252, 53
	s_add_i32 s0, s0, 64
	v_writelane_b32 v252, s0, 52
	s_waitcnt lgkmcnt(0)
	v_mfma_f32_32x32x16_bf16 v[96:111], v[12:15], v[2:5], v[96:111]
	ds_read_b128 v[12:15], v16 offset:1568
	s_cmp_eq_u32 s6, s7
	v_writelane_b32 v252, s1, 53
	s_waitcnt lgkmcnt(0)
	v_mfma_f32_32x32x16_bf16 v[112:127], v[12:15], v[2:5], v[112:127]
	ds_read_b128 v[2:5], v0 offset:1088
	v_cvt_pk_bf16_f32 v12, v28, v29
	v_cvt_pk_bf16_f32 v13, v30, v31
	s_waitcnt lgkmcnt(0)
	v_mfma_f32_32x32x16_bf16 v[96:111], v[2:5], v[6:9], v[96:111]
	ds_read_b128 v[2:5], v16 offset:1600
	s_waitcnt lgkmcnt(0)
	v_mfma_f32_32x32x16_bf16 v[112:127], v[2:5], v[6:9], v[112:127]
	ds_read_b128 v[2:5], v0 offset:1120
	s_waitcnt lgkmcnt(0)
	v_mfma_f32_32x32x16_bf16 v[96:111], v[2:5], v[10:13], v[96:111]
	ds_read_b128 v[2:5], v16 offset:1632
	s_waitcnt lgkmcnt(0)
	v_mfma_f32_32x32x16_bf16 v[112:127], v[2:5], v[10:13], v[112:127]
	s_cbranch_scc1 .LBB0_642
	v_mov_b32_e32 v129, v196
	s_branch .LBB0_628

; DI int tidx() { int t = threadIdx.x; asm volatile("" : "+v"(t)); return t; }
; DI const float* IN(int i) { return *(const float* const __attribute__((address_space(4)))*)(KA() + 8 * i); }
; DI char* WS(const Params&) { return *(char* const __attribute__((address_space(4)))*)(KA() + 8 * 30); }
; DI void swa_item(const Params& p, int l_, int item, char* smraw, bool wr = true) {
;   const int qb = 15 - (item >> 4), bg = item & 15, b = bg >> 1, g = bg & 1;
;   bf16_t* Ks = (bf16_t*)smraw; bf16_t* Vs = Ks + 64 * LDT;
;   const bf16_t* hb = (const bf16_t*)(WS(p) + O_H);
;   bf16_t* hw = (bf16_t*)(WS(p) + O_H);
;   const bf16_t* vt = (const bf16_t*)(WS(p) + O_VT);
;   const int tid = tidx(), lane = tid & 63, w = tid >> 6, h = lane >> 5, r31 = lane & 31;
;   const int H = g * 2 + (w & 1);
;   const int qpos = 128 * qb + 32 * (w >> 1) + r31;
;   const size_t mrow = (size_t)b * 2048 + qpos;
;   bf16x8 qf[4];
; #pragma unroll
;   for (int s = 0; s < 4; ++s) qf[s] = *(const bf16x8*)(hb + mrow * HS + C_BQ + H * 64 + 16 * s + 8 * h);
;   scale_q(qf);
;   const float sink = IN(10)[l_ * 4 + H] * 1.4426950408889634f;
;   f32x16 o[2];
;   zero_o(o);
;   float m = sink, l = (h == 0) ? 1.f : 0.f;
;   const int jlo = (qb >= 1) ? 2 * qb - 2 : 0;
;   attn_loop<2>(hb + (size_t)b * 2048 * HS + C_BK + g * 64, HS, vt + ((size_t)((2 * 8 + b) * 128 + g * 64)) * 2048, 2048, jlo, 2 * qb + 1, qf, qpos, 0u, 0u, 128, 128 * qb, 128 * qb + 127, o, m, l, Ks, Vs);
.LBB0_643:
	s_and_b64 vcc, exec, s[2:3]
	s_cbranch_vccz .LBB0_660
	v_readlane_b32 s10, v252, 6
	v_readlane_b32 s11, v252, 7
	s_mov_b64 s[2:3], s[10:11]
	s_load_dwordx2 s[2:3], s[2:3], 0xf0
	s_sub_i32 s0, s20, 32
	s_lshr_b32 s0, s0, 4
	s_mov_b64 s[4:5], s[10:11]
	s_bfe_u32 s6, s20, 0x30001
	s_xor_b32 s1, s0, 15
	s_waitcnt lgkmcnt(0)
	s_add_u32 s2, s2, 0x32a4500
	s_load_dwordx2 s[12:13], s[4:5], 0xf0
	s_mov_b64 s[4:5], s[10:11]
	v_mov_b32_e32 v0, v201
	s_addc_u32 s3, s3, 0
	s_lshl_b32 s7, s23, 1
	s_waitcnt vmcnt(0)
	v_lshrrev_b32_e32 v2, 6, v0
	v_and_or_b32 v131, v2, 1, s7
	v_ashrrev_i32_e32 v2, 2, v0
	s_lshl_b32 s8, s1, 7
	v_and_b32_e32 v2, 0xffffffe0, v2
	v_add_u32_e32 v2, s8, v2
	v_and_or_b32 v124, v0, 31, v2
	v_readlane_b32 s34, v252, 52
	v_readlane_b32 s35, v252, 53
	s_lshl_b32 s34, s6, 11
	v_ashrrev_i32_e32 v125, 31, v124
	v_lshl_add_u64 v[122:123], v[124:125], 0, s[34:35]
	v_mov_b64_e32 v[2:3], s[2:3]
	s_movk_i32 s22, 0x1e00
	s_mov_b32 s38, s20
	v_mad_u64_u32 v[2:3], s[20:21], v122, s22, v[2:3]
	v_bfe_u32 v130, v0, 5, 1
	v_mad_i32_i24 v3, v123, s22, v3
	v_lshlrev_b32_e32 v0, 7, v131
	v_lshl_add_u64 v[2:3], v[2:3], 0, v[0:1]
	v_lshlrev_b32_e32 v0, 4, v130
	v_lshl_add_u64 v[14:15], v[2:3], 0, v[0:1]
	s_mov_b64 s[20:21], s[10:11]
	global_load_dwordx4 v[2:5], v[14:15], off offset:3584
	global_load_dwordx4 v[6:9], v[14:15], off offset:3616
	global_load_dwordx4 v[10:13], v[14:15], off offset:3648
	s_nop 0
	global_load_dwordx4 v[14:17], v[14:15], off offset:3680
	s_load_dwordx2 s[20:21], s[20:21], 0x50
	v_readlane_b32 s7, v252, 60
	s_lshl_b32 s9, s1, 1
	s_add_i32 s1, s9, -2
	v_or_b32_e32 v0, s7, v131
	s_waitcnt lgkmcnt(0)
	v_lshl_add_u64 v[18:19], v[0:1], 2, s[20:21]
	global_load_dword v18, v[18:19], off
	s_cmp_lg_u32 s0, 15
	v_cmp_eq_u32_e32 vcc, 0, v130
	s_cselect_b32 s20, s1, 0
	s_or_b32 s0, s9, 1
	v_mov_b32_e32 v33, 0
	v_cndmask_b32_e64 v125, 0, 1.0, vcc
	v_mov_b32_e32 v19, v201
	s_cmp_gt_i32 s20, s0
	v_writelane_b32 v252, s34, 52
	s_nop 1
	v_writelane_b32 v252, s35, 53
	s_cbranch_scc1 .LBB0_756
; DI unsigned pack2(float a, float b) { fv2 v = {a, b}; return __builtin_bit_cast(unsigned, __builtin_convertvector(v, bfv2)); }
; DI float bflo(unsigned u) { return __uint_as_float(u << 16); }
; DI float bfhi(unsigned u) { return __uint_as_float(u & 0xffff0000u); }
; DI int tidx() { int t = threadIdx.x; asm volatile("" : "+v"(t)); return t; }
; template <int MODE> ...
;   const int tid = tidx(), lane = tid & 63, h = lane >> 5, r31 = lane & 31;
;   const int lr = tid >> 3, lc = (tid & 7) * 8;
;   int j = jlo;
;   if (MODE == 1) { while (j <= jhi && !((uni >> j) & 1)) ++j; }
;   uint4 k0, v0;
;   if (j <= jhi) {
;     k0 = *(const uint4*)(kb + (long)(64 * j + lr) * kstride + lc);
;     v0 = *(const uint4*)(vtb + (long)lr * vstride + 64 * j + lc);
;   }
;   while (j <= jhi) {
;     __syncthreads();
;     *(uint4*)(Ks + lr * LDT + lc) = k0;
;     *(uint4*)(Vs + lr * LDT + lc) = v0;
;     __syncthreads();
;     int jn = j + 1;
;     if (MODE == 1) { while (jn <= jhi && !((uni >> jn) & 1)) ++jn; }
;     if (jn <= jhi) {
;       k0 = *(const uint4*)(kb + (long)(64 * jn + lr) * kstride + lc);
;       v0 = *(const uint4*)(vtb + (long)lr * vstride + 64 * jn + lc);
;     }
; DI void scale_q(bf16x8 (&qf)[4]) {
; #pragma unroll
;   for (int s = 0; s < 4; ++s) {
;     const uint4 t = __builtin_bit_cast(uint4, qf[s]);
;     qf[s] = __builtin_bit_cast(bf16x8, make_uint4(pack2(bflo(t.x) * SL2, bfhi(t.x) * SL2), pack2(bflo(t.y) * SL2, bfhi(t.y) * SL2),
;                                                   pack2(bflo(t.z) * SL2, bfhi(t.z) * SL2), pack2(bflo(t.w) * SL2, bfhi(t.w) * SL2)));
;   }
; }
; DI void zero_o(f32x16 (&o)[2]) {
; #pragma unroll
;   for (int e = 0; e < 16; ++e) { o[0][e] = 0.f; o[1][e] = 0.f; }
; }
	s_load_dwordx2 s[4:5], s[4:5], 0xf0
	s_waitcnt vmcnt(1)
	v_lshlrev_b32_e32 v22, 16, v14
	v_and_b32_e32 v23, 0xffff0000, v14
	s_mov_b32 s10, 0x3e38aa3b
	v_lshlrev_b32_e32 v14, 16, v15
	v_and_b32_e32 v15, 0xffff0000, v15
	v_pk_mul_f32 v[14:15], v[14:15], s[10:11] op_sel_hi:[1,0]
	s_lshl_b32 s0, s23, 18
	v_cvt_pk_bf16_f32 v99, v14, v15
	v_lshlrev_b32_e32 v14, 16, v16
	v_and_b32_e32 v15, 0xffff0000, v16
	s_lshl_b32 s1, s6, 19
	v_pk_mul_f32 v[14:15], v[14:15], s[10:11] op_sel_hi:[1,0]
	s_or_b32 s0, s1, s0
	v_cvt_pk_bf16_f32 v100, v14, v15
	v_lshlrev_b32_e32 v14, 16, v17
	v_and_b32_e32 v15, 0xffff0000, v17
	s_waitcnt lgkmcnt(0)
	s_add_u32 s4, s4, s0
	v_pk_mul_f32 v[14:15], v[14:15], s[10:11] op_sel_hi:[1,0]
	s_addc_u32 s5, s5, 0
	s_mul_i32 s0, s34, 0x1e00
	v_cvt_pk_bf16_f32 v101, v14, v15
	v_lshlrev_b32_e32 v14, 16, v10
	v_and_b32_e32 v15, 0xffff0000, v10
	v_lshlrev_b32_e32 v10, 16, v11
	v_and_b32_e32 v11, 0xffff0000, v11
	s_add_u32 s0, s2, s0
	v_pk_mul_f32 v[10:11], v[10:11], s[10:11] op_sel_hi:[1,0]
	s_addc_u32 s1, s3, 0
	s_lshl_b32 s2, s23, 7
	v_cvt_pk_bf16_f32 v103, v10, v11
	v_lshlrev_b32_e32 v10, 16, v12
	v_and_b32_e32 v11, 0xffff0000, v12
	s_add_u32 s0, s0, s2
	v_pk_mul_f32 v[10:11], v[10:11], s[10:11] op_sel_hi:[1,0]
	s_addc_u32 s1, s1, 0
	v_cvt_pk_bf16_f32 v104, v10, v11
	v_lshlrev_b32_e32 v10, 16, v13
	v_and_b32_e32 v11, 0xffff0000, v13
	s_add_u32 s6, s0, 0x1000
	v_ashrrev_i32_e32 v20, 3, v19
	v_pk_mul_f32 v[10:11], v[10:11], s[10:11] op_sel_hi:[1,0]
	s_addc_u32 s7, s1, 0
	s_lshl_b32 s2, s20, 6
	v_cvt_pk_bf16_f32 v105, v10, v11
	v_add_u32_e32 v0, s2, v20
	v_mov_b64_e32 v[10:11], s[6:7]
	v_mad_i64_i32 v[10:11], s[22:23], v0, s22, v[10:11]
	v_lshlrev_b32_e32 v0, 4, v19
	v_and_b32_e32 v0, 0x70, v0
	v_lshl_add_u64 v[10:11], v[10:11], 0, v[0:1]
	v_ashrrev_i32_e32 v21, 31, v20
	global_load_dwordx4 v[106:109], v[10:11], off
	v_lshlrev_b64 v[10:11], 12, v[20:21]
	v_lshl_add_u64 v[10:11], s[4:5], 0, v[10:11]
	s_mov_b64 s[4:5], 0xb2a4500
	v_lshl_add_u64 v[10:11], v[10:11], 0, s[4:5]
	s_ashr_i32 s3, s2, 31
	v_lshl_add_u64 v[12:13], s[2:3], 1, v[10:11]
	v_lshl_add_u64 v[12:13], v[12:13], 0, v[0:1]
	global_load_dwordx4 v[114:117], v[12:13], off
	v_lshlrev_b32_e32 v12, 16, v6
	v_and_b32_e32 v13, 0xffff0000, v6
	v_lshlrev_b32_e32 v6, 16, v7
	v_and_b32_e32 v7, 0xffff0000, v7
	v_pk_mul_f32 v[6:7], v[6:7], s[10:11] op_sel_hi:[1,0]
	s_movk_i32 s0, 0x90
	v_cvt_pk_bf16_f32 v111, v6, v7
	v_lshlrev_b32_e32 v6, 16, v8
	v_and_b32_e32 v7, 0xffff0000, v8
	v_pk_mul_f32 v[6:7], v[6:7], s[10:11] op_sel_hi:[1,0]
	v_pk_mul_f32 v[22:23], v[22:23], s[10:11] op_sel_hi:[1,0]
	v_cvt_pk_bf16_f32 v112, v6, v7
	v_lshlrev_b32_e32 v6, 16, v9
	v_and_b32_e32 v7, 0xffff0000, v9
	v_pk_mul_f32 v[6:7], v[6:7], s[10:11] op_sel_hi:[1,0]
	v_pk_mul_f32 v[14:15], v[14:15], s[10:11] op_sel_hi:[1,0]
	v_cvt_pk_bf16_f32 v113, v6, v7
	v_lshlrev_b32_e32 v6, 16, v2
	v_and_b32_e32 v7, 0xffff0000, v2
	v_lshlrev_b32_e32 v2, 16, v3
	v_and_b32_e32 v3, 0xffff0000, v3
	v_pk_mul_f32 v[2:3], v[2:3], s[10:11] op_sel_hi:[1,0]
	v_pk_mul_f32 v[12:13], v[12:13], s[10:11] op_sel_hi:[1,0]
	v_cvt_pk_bf16_f32 v119, v2, v3
	v_lshlrev_b32_e32 v2, 16, v4
	v_and_b32_e32 v3, 0xffff0000, v4
	v_pk_mul_f32 v[2:3], v[2:3], s[10:11] op_sel_hi:[1,0]
	v_mul_lo_u32 v4, v20, s0
	v_cvt_pk_bf16_f32 v120, v2, v3
	v_lshlrev_b32_e32 v2, 16, v5
	v_and_b32_e32 v3, 0xffff0000, v5
	v_pk_mul_f32 v[2:3], v[2:3], s[10:11] op_sel_hi:[1,0]
	v_pk_mul_f32 v[6:7], v[6:7], s[10:11] op_sel_hi:[1,0]
	v_cvt_pk_bf16_f32 v121, v2, v3
	v_bfe_u32 v3, v19, 5, 1
	v_and_b32_e32 v2, 31, v19
	v_add3_u32 v132, 0, v0, v4
	v_lshl_add_u64 v[126:127], s[6:7], 0, v[0:1]
	v_lshl_add_u64 v[128:129], v[10:11], 0, v[0:1]
	v_lshl_add_u32 v133, v3, 4, 0
	v_lshlrev_b32_e32 v0, 3, v3
	v_cvt_pk_bf16_f32 v98, v22, v23
	v_cvt_pk_bf16_f32 v102, v14, v15
	v_cvt_pk_bf16_f32 v110, v12, v13
	v_cvt_pk_bf16_f32 v118, v6, v7
	s_waitcnt vmcnt(2)
	v_mul_f32_e32 v66, 0x3fb8aa3b, v18
	v_lshlrev_b32_e32 v134, 2, v3
	v_sub_u32_e32 v32, v133, v0
	v_mul_u32_u24_e32 v136, 0x90, v2
	v_add_u32_e32 v137, 64, v20
	v_mov_b32_e32 v2, v1
	v_mov_b32_e32 v3, v1
	v_mov_b32_e32 v4, v1
	v_mov_b32_e32 v5, v1
	v_mov_b32_e32 v6, v1
	v_mov_b32_e32 v7, v1
	v_mov_b32_e32 v8, v1
	v_mov_b32_e32 v9, v1
	v_mov_b32_e32 v10, v1
	v_mov_b32_e32 v11, v1
	v_mov_b32_e32 v12, v1
	v_mov_b32_e32 v13, v1
	v_mov_b32_e32 v14, v1
	v_mov_b32_e32 v15, v1
	v_mov_b32_e32 v16, v1
	v_mov_b32_e32 v17, v1
	v_mov_b32_e32 v18, v1
	v_mov_b32_e32 v19, v1
	v_mov_b32_e32 v20, v1
	v_mov_b32_e32 v21, v1
	v_mov_b32_e32 v22, v1
	v_mov_b32_e32 v23, v1
	v_mov_b32_e32 v24, v1
	v_mov_b32_e32 v25, v1
	v_mov_b32_e32 v26, v1
	v_mov_b32_e32 v27, v1
	v_mov_b32_e32 v28, v1
	v_mov_b32_e32 v29, v1
	v_mov_b32_e32 v30, v1
	v_mov_b32_e32 v31, v1
	v_mov_b32_e32 v0, v1
	v_add_u32_e32 v138, v133, v136
	v_mov_b64_e32 v[32:33], v[30:31]
	s_movk_i32 s1, 0x1e00
	v_add_u32_e32 v135, 0xffffff80, v124
	v_mov_b64_e32 v[30:31], v[28:29]
	v_mov_b64_e32 v[28:29], v[26:27]
	v_mov_b64_e32 v[26:27], v[24:25]
	v_mov_b64_e32 v[24:25], v[22:23]
	v_mov_b64_e32 v[22:23], v[20:21]
	v_mov_b64_e32 v[20:21], v[18:19]
	v_mov_b64_e32 v[18:19], v[16:17]
	v_mov_b64_e32 v[16:17], v[14:15]
	v_mov_b64_e32 v[14:15], v[12:13]
	v_mov_b64_e32 v[12:13], v[10:11]
	v_mov_b64_e32 v[10:11], v[8:9]
	v_mov_b64_e32 v[8:9], v[6:7]
	v_mov_b64_e32 v[6:7], v[4:5]
	v_mov_b64_e32 v[4:5], v[2:3]
	v_mov_b64_e32 v[2:3], v[0:1]
.LBB0_646:
	s_cmp_gt_i32 s20, s9
	s_cselect_b64 s[4:5], -1, 0
	s_and_b64 vcc, exec, s[4:5]
	s_barrier
	s_waitcnt vmcnt(1)
	ds_write_b128 v132, v[106:109]
	s_waitcnt vmcnt(0)
	v_and_b32_e32 v246, 1, v201
	v_lshlrev_b32_e32 v246, 3, v246
	v_sub_u32_e32 v246, v132, v246
	v_add_u32_e32 v246, 0x2400, v246
	ds_write2_b64 v246, v[114:115], v[116:117] offset1:2
	s_waitcnt lgkmcnt(0)
	s_barrier
	s_cbranch_vccnz .LBB0_648
	s_add_i32 s6, s2, 64
	v_add_u32_e32 v0, s2, v137
	v_mad_i64_i32 v[34:35], s[22:23], v0, s1, v[126:127]
	s_ashr_i32 s7, s6, 31
	global_load_dwordx4 v[106:109], v[34:35], off
	v_lshl_add_u64 v[34:35], s[6:7], 1, v[128:129]
	global_load_dwordx4 v[114:117], v[34:35], off

; #define MFMA32(a, b, c) __builtin_amdgcn_mfma_f32_32x32x16_bf16((a), (b), (c), 0, 0, 0)
; DI unsigned pack2(float a, float b) { fv2 v = {a, b}; return __builtin_bit_cast(unsigned, __builtin_convertvector(v, bfv2)); }
; template <int MODE> ...
;     ...
; #pragma unroll
;     for (int kt = 0; kt < 2; ++kt)
; #pragma unroll
;       for (int sp = 0; sp < 2; ++sp) {
;         const bf16x8 fb = __builtin_bit_cast(bf16x8, make_uint4(pack2(s[kt][8 * sp + 0], s[kt][8 * sp + 1]), pack2(s[kt][8 * sp + 2], s[kt][8 * sp + 3]),
;                                                                pack2(s[kt][8 * sp + 4], s[kt][8 * sp + 5]), pack2(s[kt][8 * sp + 6], s[kt][8 * sp + 7])));
; #pragma unroll
;         for (int dt = 0; dt < 2; ++dt) {
;           const bf16_t* vr = Vs + (32 * dt + r31) * LDT + 32 * kt + 16 * sp + 4 * h;
;           const uint2 lo = *(const uint2*)vr; const uint2 hi = *(const uint2*)(vr + 8);
;           const bf16x8 fa = __builtin_bit_cast(bf16x8, make_uint4(lo.x, lo.y, hi.x, hi.y));
;           o[dt] = MFMA32(fa, fb, o[dt]);
;         }
;       }
.LBB0_658:
	v_add_u32_e32 v0, 0x2000, v138
	v_add_u32_e32 v70, 0x3000, v138
	ds_read_b128 v[66:69], v0 offset:1024
	v_cvt_pk_bf16_f32 v34, v34, v35
	v_cvt_pk_bf16_f32 v35, v36, v37
	v_cvt_pk_bf16_f32 v36, v38, v39
	v_cvt_pk_bf16_f32 v37, v40, v41
	ds_read_b128 v[38:41], v70 offset:1536
	s_add_i32 s20, s20, 1
	s_add_i32 s2, s2, 64
	s_waitcnt lgkmcnt(1)
	v_mfma_f32_32x32x16_bf16 v[2:17], v[66:69], v[34:37], v[2:17]
	s_andn2_b64 vcc, exec, s[4:5]
	s_waitcnt lgkmcnt(0)
	v_mfma_f32_32x32x16_bf16 v[18:33], v[38:41], v[34:37], v[18:33]
	ds_read_b128 v[34:37], v0 offset:1056
	v_cvt_pk_bf16_f32 v38, v42, v43
	v_cvt_pk_bf16_f32 v39, v44, v45
	v_cvt_pk_bf16_f32 v40, v46, v47
	v_cvt_pk_bf16_f32 v41, v48, v49
	s_waitcnt lgkmcnt(0)
	s_nop 0
	v_mfma_f32_32x32x16_bf16 v[2:17], v[34:37], v[38:41], v[2:17]
	ds_read_b128 v[34:37], v70 offset:1568
	s_waitcnt lgkmcnt(0)
	v_mfma_f32_32x32x16_bf16 v[18:33], v[34:37], v[38:41], v[18:33]
	ds_read_b128 v[34:37], v0 offset:1088
	v_cvt_pk_bf16_f32 v38, v50, v51
	v_cvt_pk_bf16_f32 v39, v52, v53
	v_cvt_pk_bf16_f32 v40, v54, v55
	v_cvt_pk_bf16_f32 v41, v56, v57
	s_waitcnt lgkmcnt(0)
	s_nop 0
	v_mfma_f32_32x32x16_bf16 v[2:17], v[34:37], v[38:41], v[2:17]
	ds_read_b128 v[34:37], v70 offset:1600
	s_waitcnt lgkmcnt(0)
	v_mfma_f32_32x32x16_bf16 v[18:33], v[34:37], v[38:41], v[18:33]
	ds_read_b128 v[34:37], v0 offset:1120
	v_cvt_pk_bf16_f32 v38, v58, v59
	v_cvt_pk_bf16_f32 v39, v60, v61
	v_cvt_pk_bf16_f32 v40, v62, v63
	v_cvt_pk_bf16_f32 v41, v64, v65
	s_waitcnt lgkmcnt(0)
	s_nop 0
	v_mfma_f32_32x32x16_bf16 v[2:17], v[34:37], v[38:41], v[2:17]
	ds_read_b128 v[34:37], v70 offset:1632
	s_waitcnt lgkmcnt(0)
	v_mfma_f32_32x32x16_bf16 v[18:33], v[34:37], v[38:41], v[18:33]
	s_cbranch_vccz .LBB0_757
	v_mov_b32_e32 v66, v139
	s_branch .LBB0_646
